# conv_weights inner loop rewritten (8+8 loads in flight per wait) on top of LRU/merge-gate/SSD edits
# speedup vs baseline: 1.0451x; 1.0451x over previous
; __device__ __forceinline__ void conv_weights(PP P, int l, bf16_t* W, int tid_, int bid_, int ngt, LAS unsigned char* lds) {
;     ...
;         const int kh = lane >> 5;
; #pragma unroll 8
;         for (int i = 0; i < 32; ++i) { const int kk = 2 * i + kh; float x = 0.f; if (valid) { x = ptr[(size_t)kk * stride] * sn; if (gk) x *= gk[kk]; } scr[kk * 33 + (lane & 31)] = x; }
.LBB0_133:
	s_or_b64 exec, exec, s[66:67]
	s_add_u32 s64, s64, 64
	s_addc_u32 s65, s65, 0
	s_nop 0
	v_add_u32_e32 v0, 0x840, v0
	s_cmpk_eq_i32 s64, 0x100
	v_lshl_add_u64 v[28:29], v[28:29], 0, v[36:37]
	s_cbranch_scc1 .LBB0_24
.LBB0_134:
	v_mov_b32_e32 v52, 0
	v_mov_b32_e32 v53, 0
	v_mov_b32_e32 v54, 0
	v_mov_b32_e32 v55, 0
	v_mov_b32_e32 v56, 0
	v_mov_b32_e32 v57, 0
	v_mov_b32_e32 v58, 0
	v_mov_b32_e32 v59, 0
	v_mov_b32_e32 v60, 1.0
	v_mov_b32_e32 v61, 1.0
	v_mov_b32_e32 v62, 1.0
	v_mov_b32_e32 v63, 1.0
	v_mov_b32_e32 v64, 1.0
	v_mov_b32_e32 v65, 1.0
	v_mov_b32_e32 v66, 1.0
	v_mov_b32_e32 v67, 1.0
	s_and_saveexec_b64 s[66:67], s[6:7]
	s_cbranch_execz .Lcw_st
	v_lshl_add_u64 v[34:35], v[28:29], 0, v[50:51]
	global_load_dword v52, v[34:35], off
	v_lshl_add_u64 v[34:35], v[28:29], 0, v[48:49]
	global_load_dword v53, v[34:35], off
	v_lshl_add_u64 v[34:35], v[28:29], 0, v[46:47]
	global_load_dword v54, v[34:35], off
	v_lshl_add_u64 v[34:35], v[28:29], 0, v[44:45]
	global_load_dword v55, v[34:35], off
	v_lshl_add_u64 v[34:35], v[28:29], 0, v[42:43]
	global_load_dword v56, v[34:35], off
	v_lshl_add_u64 v[34:35], v[28:29], 0, v[40:41]
	global_load_dword v57, v[34:35], off
	v_lshl_add_u64 v[34:35], v[28:29], 0, v[38:39]
	global_load_dword v58, v[34:35], off
	v_lshl_add_u64 v[34:35], v[28:29], 0, v[30:31]
	global_load_dword v59, v[34:35], off
	s_and_saveexec_b64 s[68:69], vcc
	s_cbranch_execz .Lcw_ng
	v_lshl_add_u64 v[34:35], v[32:33], 0, s[64:65]
	global_load_dword v60, v[34:35], off
	global_load_dword v61, v[34:35], off offset:8
	global_load_dword v62, v[34:35], off offset:16
	global_load_dword v63, v[34:35], off offset:24
	global_load_dword v64, v[34:35], off offset:32
	global_load_dword v65, v[34:35], off offset:40
	global_load_dword v66, v[34:35], off offset:48
	global_load_dword v67, v[34:35], off offset:56
.Lcw_ng:
	s_or_b64 exec, exec, s[68:69]
	s_waitcnt vmcnt(0)
	v_mul_f32_e32 v52, v21, v52
	v_mul_f32_e32 v53, v21, v53
	v_mul_f32_e32 v54, v21, v54
	v_mul_f32_e32 v55, v21, v55
	v_mul_f32_e32 v56, v21, v56
	v_mul_f32_e32 v57, v21, v57
	v_mul_f32_e32 v58, v21, v58
	v_mul_f32_e32 v59, v21, v59
	v_mul_f32_e32 v52, v52, v60
	v_mul_f32_e32 v53, v53, v61
	v_mul_f32_e32 v54, v54, v62
	v_mul_f32_e32 v55, v55, v63
	v_mul_f32_e32 v56, v56, v64
	v_mul_f32_e32 v57, v57, v65
	v_mul_f32_e32 v58, v58, v66
	v_mul_f32_e32 v59, v59, v67
.Lcw_st:
	s_or_b64 exec, exec, s[66:67]
	ds_write_b32 v0, v52
	ds_write_b32 v0, v53 offset:264
	ds_write_b32 v0, v54 offset:528
	ds_write_b32 v0, v55 offset:792
	ds_write_b32 v0, v56 offset:1056
	ds_write_b32 v0, v57 offset:1320
	ds_write_b32 v0, v58 offset:1584
	ds_write_b32 v0, v59 offset:1848
	s_branch .LBB0_133
